# nt (streaming) hint on the final f32 output stores of the last phase
# speedup vs baseline: 1.0052x; 1.0043x over previous
.LBB0_1627:
	v_add_co_u32_e32 v72, vcc, s16, v34
	s_add_u32 s0, s4, s14
	v_lshl_add_u64 v[40:41], s[4:5], 0, v[36:37]
	v_addc_co_u32_e32 v73, vcc, -1, v35, vcc
	s_addc_u32 s1, s5, s15
	v_add_co_u32_e32 v40, vcc, s7, v40
	s_add_i32 s2, s2, s6
	s_nop 0
	v_addc_co_u32_e32 v41, vcc, 0, v41, vcc
	global_load_dword v39, v33, s[0:1]
	global_load_dwordx2 v[42:43], v[40:41], off
	global_load_dwordx2 v[44:45], v[40:41], off offset:512
	global_load_dwordx2 v[46:47], v[40:41], off offset:1024
	global_load_dwordx2 v[48:49], v[40:41], off offset:1536
	global_load_dwordx2 v[50:51], v[40:41], off offset:2048
	global_load_dwordx2 v[52:53], v[40:41], off offset:2560
	global_load_dwordx2 v[54:55], v[40:41], off offset:3072
	global_load_dwordx2 v[56:57], v[40:41], off offset:3584
	s_add_u32 s14, s14, s8
	s_addc_u32 s15, s15, s9
	v_lshl_add_u64 v[36:37], v[36:37], 0, s[12:13]
	s_cmpk_gt_i32 s2, 0x7fff
	s_waitcnt vmcnt(8)
	v_fmamk_f32 v39, v39, 0x3a000000, v32
	v_mul_f32_e32 v74, 0x4f800000, v39
	v_cmp_gt_f32_e32 vcc, s3, v39
	s_waitcnt vmcnt(7)
	v_lshlrev_b32_e32 v40, 16, v42
	v_and_b32_e32 v41, 0xffff0000, v42
	v_cndmask_b32_e32 v39, v39, v74, vcc
	v_sqrt_f32_e32 v74, v39
	v_lshlrev_b32_e32 v42, 16, v43
	v_and_b32_e32 v43, 0xffff0000, v43
	s_waitcnt vmcnt(6)
	v_lshlrev_b32_e32 v58, 16, v44
	v_add_u32_e32 v75, -1, v74
	v_add_u32_e32 v76, 1, v74
	v_fma_f32 v77, -v75, v74, v39
	v_fma_f32 v78, -v76, v74, v39
	v_cmp_ge_f32_e64 s[0:1], 0, v77
	v_and_b32_e32 v59, 0xffff0000, v44
	v_lshlrev_b32_e32 v44, 16, v45
	v_cndmask_b32_e64 v74, v74, v75, s[0:1]
	v_cmp_lt_f32_e64 s[0:1], 0, v78
	v_and_b32_e32 v45, 0xffff0000, v45
	s_waitcnt vmcnt(5)
	v_lshlrev_b32_e32 v60, 16, v46
	v_cndmask_b32_e64 v74, v74, v76, s[0:1]
	v_mul_f32_e32 v75, 0x37800000, v74
	v_cndmask_b32_e32 v74, v74, v75, vcc
	v_cmp_class_f32_e32 vcc, v39, v38
	v_and_b32_e32 v61, 0xffff0000, v46
	v_lshlrev_b32_e32 v46, 16, v47
	v_cndmask_b32_e32 v39, v74, v39, vcc
	v_div_scale_f32 v74, s[0:1], v39, v39, 1.0
	v_rcp_f32_e32 v76, v74
	v_div_scale_f32 v75, vcc, 1.0, v39, 1.0
	v_and_b32_e32 v47, 0xffff0000, v47
	v_fma_f32 v77, -v74, v76, 1.0
	v_fmac_f32_e32 v76, v77, v76
	v_mul_f32_e32 v77, v75, v76
	v_fma_f32 v78, -v74, v77, v75
	v_fmac_f32_e32 v77, v78, v76
	v_fma_f32 v74, -v74, v77, v75
	v_div_fmas_f32 v74, v74, v76, v77
	v_div_fixup_f32 v74, v74, v39, 1.0
	s_waitcnt vmcnt(4)
	v_lshlrev_b32_e32 v62, 16, v48
	v_and_b32_e32 v63, 0xffff0000, v48
	v_lshlrev_b32_e32 v48, 16, v49
	v_and_b32_e32 v49, 0xffff0000, v49
	s_waitcnt vmcnt(3)
	v_lshlrev_b32_e32 v64, 16, v50
	v_and_b32_e32 v65, 0xffff0000, v50
	v_lshlrev_b32_e32 v50, 16, v51
	v_and_b32_e32 v51, 0xffff0000, v51
	s_waitcnt vmcnt(2)
	v_lshlrev_b32_e32 v66, 16, v52
	v_and_b32_e32 v67, 0xffff0000, v52
	v_lshlrev_b32_e32 v52, 16, v53
	v_and_b32_e32 v53, 0xffff0000, v53
	s_waitcnt vmcnt(1)
	v_lshlrev_b32_e32 v68, 16, v54
	v_and_b32_e32 v69, 0xffff0000, v54
	v_lshlrev_b32_e32 v54, 16, v55
	v_and_b32_e32 v55, 0xffff0000, v55
	s_waitcnt vmcnt(0)
	v_lshlrev_b32_e32 v70, 16, v56
	v_and_b32_e32 v71, 0xffff0000, v56
	v_lshlrev_b32_e32 v56, 16, v57
	v_and_b32_e32 v57, 0xffff0000, v57
	v_pk_mul_f32 v[40:41], v[74:75], v[40:41] op_sel_hi:[0,1]
	v_pk_mul_f32 v[42:43], v[74:75], v[42:43] op_sel_hi:[0,1]
	v_pk_mul_f32 v[58:59], v[74:75], v[58:59] op_sel_hi:[0,1]
	v_pk_mul_f32 v[76:77], v[74:75], v[44:45] op_sel_hi:[0,1]
	v_pk_mul_f32 v[60:61], v[74:75], v[60:61] op_sel_hi:[0,1]
	v_pk_mul_f32 v[78:79], v[74:75], v[46:47] op_sel_hi:[0,1]
	v_pk_mul_f32 v[62:63], v[74:75], v[62:63] op_sel_hi:[0,1]
	v_pk_mul_f32 v[80:81], v[74:75], v[48:49] op_sel_hi:[0,1]
	v_pk_mul_f32 v[64:65], v[74:75], v[64:65] op_sel_hi:[0,1]
	v_pk_mul_f32 v[82:83], v[74:75], v[50:51] op_sel_hi:[0,1]
	v_pk_mul_f32 v[66:67], v[74:75], v[66:67] op_sel_hi:[0,1]
	v_pk_mul_f32 v[84:85], v[74:75], v[52:53] op_sel_hi:[0,1]
	v_pk_mul_f32 v[68:69], v[74:75], v[68:69] op_sel_hi:[0,1]
	v_pk_mul_f32 v[86:87], v[74:75], v[54:55] op_sel_hi:[0,1]
	v_pk_mul_f32 v[70:71], v[74:75], v[70:71] op_sel_hi:[0,1]
	v_pk_mul_f32 v[74:75], v[74:75], v[56:57] op_sel_hi:[0,1]
	v_pk_mul_f32 v[40:41], v[28:29], v[40:41]
	v_pk_mul_f32 v[42:43], v[30:31], v[42:43]
	v_pk_mul_f32 v[44:45], v[24:25], v[58:59]
	v_pk_mul_f32 v[46:47], v[26:27], v[76:77]
	v_pk_mul_f32 v[48:49], v[20:21], v[60:61]
	v_pk_mul_f32 v[50:51], v[22:23], v[78:79]
	v_pk_mul_f32 v[52:53], v[16:17], v[62:63]
	v_pk_mul_f32 v[54:55], v[18:19], v[80:81]
	v_pk_mul_f32 v[56:57], v[12:13], v[64:65]
	v_pk_mul_f32 v[58:59], v[14:15], v[82:83]
	v_pk_mul_f32 v[60:61], v[8:9], v[66:67]
	v_pk_mul_f32 v[62:63], v[10:11], v[84:85]
	v_pk_mul_f32 v[64:65], v[4:5], v[68:69]
	v_pk_mul_f32 v[66:67], v[6:7], v[86:87]
	v_pk_mul_f32 v[68:69], v[0:1], v[70:71]
	v_pk_mul_f32 v[70:71], v[2:3], v[74:75]
	global_store_dwordx4 v[72:73], v[40:43], off offset:-3072 nt
	global_store_dwordx4 v[72:73], v[44:47], off offset:-2048 nt
	global_store_dwordx4 v[72:73], v[48:51], off offset:-1024 nt
	global_store_dwordx4 v[34:35], v[52:55], off offset:-4096 nt
	global_store_dwordx4 v[34:35], v[56:59], off offset:-3072 nt
	global_store_dwordx4 v[34:35], v[60:63], off offset:-2048 nt
	global_store_dwordx4 v[34:35], v[64:67], off offset:-1024 nt
	global_store_dwordx4 v[34:35], v[68:71], off nt
	v_lshl_add_u64 v[34:35], v[34:35], 0, s[10:11]
	s_cbranch_scc0 .LBB0_1627
